# GEMM phase prologues: K-tile 1 half-tile stages issued before the first wait/barrier (both K-tiles' DMA latencies overlap)
# speedup vs baseline: 1.0130x; 1.0001x over previous
; #define PG8_STAGE(bufoff, gbase, voff) do { _Pragma("unroll") for (int _i = 0; _i < 2; ++_i) \
;         __builtin_amdgcn_global_load_lds((const unsigned*)((const char*)(gbase) + (voff)[_i]), (PG8_LAS unsigned*)(lds + (bufoff) + ldsw + _i * 8192), 16, 0, 0); } while (0)
; #define PG8_WAIT_V(n) asm volatile("s_waitcnt vmcnt(" #n ")" ::: "memory")
; #define PG8_BAR __builtin_amdgcn_s_barrier()
; template <class Epi, class Sched, bool ALIGN_EPI = false, bool SP2 = false>
; __device__ __forceinline__ void gemm_phase(PG8_LAS unsigned char* lds, const Gemm g, const Sched& S, const Epi& E) {
;     const int tid = threadIdx.x, wid = __builtin_amdgcn_readfirstlane(tid >> 6), lane = tid & 63, wr = wid >> 2, wc = wid & 3, fr = lane & 15, fq = lane >> 4;
;     const int K = g.K, nt1 = K / BK, nt0 = g.K0 ? g.K0 / BK : nt1;
;     unsigned voffA[2], voffB[2];
; #pragma unroll
;     for (int i = 0; i < 2; ++i) { int R, C; stage_rc(tid * 16 + i * 8192, R, C); const int Rb = Epi::PERM ? ((R & ~31) + perm32(R & 31)) : R;
;         voffA[i] = (unsigned)(R * K + C) * 2u; voffB[i] = (unsigned)(Rb * K + C) * 2u; }
;     const size_t kstep = (size_t)(BK * 2);
;     const size_t hstep = (size_t)HALF * K * 2;
;     const size_t tstep = 2 * hstep;
;     const unsigned ldsw = (unsigned)wid * 1024u;
;     const int aoff = lds_byte(wr * 64 + fr, fq * 8), boff = lds_byte(wc * 32 + fr, fq * 8);
;     ...
;     if constexpr (SP2) {
;         PG8_STAGE(PG8_SB(0, 0), cB, voffB); PG8_STAGE(PG8_SB(0, 1), cB + hstep, voffB); PG8_STAGE(PG8_SA(0, 0), cA, voffA); PG8_STAGE(PG8_SA(0, 1), cA + hstep, voffA);
;         if (wr == 1) PG8_BAR;
;         PG8_WAIT_V(2); PG8_BAR;
;         PG8_STAGE(PG8_SB(1, 0), cB + kstep, voffB); PG8_STAGE(PG8_SA(1, 0), cA + kstep, voffA); PG8_STAGE(PG8_SB(1, 1), cB + hstep + kstep, voffB);
;         PG8_WAIT_V(6); PG8_BAR;
.LBB9_222:
	s_add_u32 s8, s90, 0x7300000
	s_addc_u32 s9, s91, 0
	s_add_u32 s10, s90, 0x6a00000
	s_addc_u32 s11, s91, 0
	s_add_u32 s12, s90, 0x8300000
	s_addc_u32 s13, s91, 0
	s_add_u32 s50, s90, 0x4200000
	s_mov_b64 s[16:17], 0x80
	s_addc_u32 s51, s91, 0
	s_and_b32 s52, s1, 3
	s_add_i32 m0, s31, 0x18000
	v_lshl_add_u64 v[6:7], v[6:7], 0, s[16:17]
	s_sext_i32_i8 s33, s0
	s_lshl_b32 s53, s3, 6
	s_lshl_b32 s0, s3, 13
	s_lshl_b32 s4, s52, 5
	s_lshl_b32 s20, s52, 12
	global_load_lds_dwordx4 v[6:7], off
	v_lshl_add_u64 v[4:5], v[4:5], 0, s[16:17]
	s_add_i32 m0, s31, 0x1a000
	s_add_i32 s54, s31, 0x8000
	s_add_i32 s55, s31, 0xa000
	global_load_lds_dwordx4 v[4:5], off
	v_lshl_add_u64 v[0:1], v[0:1], 0, s[16:17]
	s_mov_b32 m0, s54
	s_add_u32 s18, s36, 0x40080
	global_load_lds_dwordx4 v[0:1], off
	v_lshl_add_u64 v[0:1], v[2:3], 0, s[16:17]
	s_mov_b32 m0, s55
	s_addc_u32 s19, s37, 0
	global_load_lds_dwordx4 v[0:1], off
	s_add_i32 m0, s31, 0x1c000
	v_lshl_add_u64 v[0:1], s[18:19], 0, v[154:155]
	global_load_lds_dwordx4 v[0:1], off
	v_lshl_add_u64 v[0:1], s[18:19], 0, v[158:159]
	s_add_i32 m0, s31, 0x1e000
	v_and_b32_e32 v171, 15, v208
	global_load_lds_dwordx4 v[0:1], off
	s_waitcnt vmcnt(8)
	s_barrier
	s_waitcnt lgkmcnt(0)
	v_lshlrev_b32_e32 v12, 4, v44
	v_lshlrev_b32_e32 v0, 2, v208
	v_lshl_or_b32 v13, v171, 6, v12
	v_and_b32_e32 v0, 32, v0
	v_bitop3_b32 v1, v13, s0, v0 bitop3:0xde
	v_lshlrev_b32_e32 v0, 6, v208
	s_movk_i32 s0, 0x3c0
	s_cmpk_lt_u32 s2, 0x100
	v_readlane_b32 s56, v251, 16
	v_and_or_b32 v0, v0, s0, v12
	s_cselect_b64 s[18:19], -1, 0
	s_add_i32 s82, s53, 0x80
	s_lshl_b32 s0, s3, 12
	s_lshl_b32 s2, s52, 10
	s_bfe_u32 s84, s1, 0x10001
	s_ashr_i32 s85, s94, 31
	v_readlane_b32 s58, v251, 18
	v_bitop3_b32 v181, s20, v0, v46 bitop3:0xf6
	v_readlane_b32 s59, v251, 19
	s_add_u32 s20, s58, 0x1000
	s_addc_u32 s21, s59, 0
	s_add_i32 s0, s0, 0
	v_and_b32_e32 v0, 3, v208
	s_add_i32 s0, s0, s2
	v_and_or_b32 v0, v45, 8, v0
	s_add_i32 s0, s0, 0x20000
	v_lshlrev_b32_e32 v3, 1, v0
	v_and_b32_e32 v4, 8, v208
	v_lshl_add_u32 v5, v44, 8, s0
	v_add3_u32 v192, v5, v4, v3
	v_lshl_add_u32 v193, v170, 4, s0
	s_add_i32 s0, 0, 0x22000
	v_lshlrev_b32_e32 v3, 8, v208
	v_add_u32_e32 v194, s0, v12
	s_lshl_b32 s0, s52, 7
	v_and_b32_e32 v3, 0x38000, v3
	v_lshlrev_b32_e32 v4, 11, v10
	v_lshrrev_b32_e32 v0, 1, v170
	s_add_u32 s0, s90, s0
	v_or3_b32 v3, v8, v3, v4
	v_and_or_b32 v190, s4, 32, v0
	v_lshlrev_b32_e32 v0, 3, v208
	v_and_b32_e32 v2, 16, v208
	v_readlane_b32 s60, v251, 20
	s_addc_u32 s1, s91, 0
	v_add_u32_e32 v164, v3, v9
	v_lshlrev_b32_e32 v3, 4, v11
	s_waitcnt vmcnt(6)
	v_and_b32_e32 v0, 8, v0
	v_cmp_eq_u32_e32 vcc, 0, v2
	v_readlane_b32 s61, v251, 21
	v_readlane_b32 s62, v251, 22
	v_readlane_b32 s63, v251, 23
	s_add_u32 s60, s0, 0x6200000
	v_and_b32_e32 v3, 0xffff8000, v3
	v_or_b32_e32 v180, s53, v171
	v_lshl_or_b32 v182, v44, 3, s4
	v_cndmask_b32_e64 v2, 12, 0, vcc
	s_addc_u32 s61, s1, 0
	v_or3_b32 v3, v8, v3, v4
	s_add_i32 s62, 0, 0x10000
	s_add_i32 s63, 0, 0x14000
	v_lshlrev_b32_e32 v160, 1, v0
	v_mbcnt_lo_u32_b32 v0, -1, 0
	v_or_b32_e32 v183, 0xfffffc00, v182
	v_or_b32_e32 v184, 16, v180
	v_or_b32_e32 v185, 32, v180
	v_or_b32_e32 v186, 48, v180
	v_or_b32_e32 v187, 16, v171
	v_or_b32_e32 v188, 32, v171
	v_or_b32_e32 v189, 48, v171
	v_lshlrev_b32_e32 v162, 2, v44
	v_mov_b32_e32 v163, v161
	v_lshlrev_b32_e32 v191, 4, v171
	s_mov_b32 s86, s94
	v_mov_b32_e32 v165, v161
	v_add_u32_e32 v166, v3, v9
	v_mov_b32_e32 v167, v161
	v_mov_b64_e32 v[168:169], 0x400
	v_mov_b64_e32 v[172:173], 0x3ff
	v_add_u32_e32 v195, s62, v181
	v_add_u32_e32 v196, s63, v181
	v_add_u32_e32 v197, 0, v1
	v_lshlrev_b32_e32 v174, 1, v2
	v_mov_b32_e32 v198, 0x358637bd
	v_mov_b32_e32 v199, 0x3e38aa3b
	v_mbcnt_hi_u32_b32 v200, -1, v0
	s_mov_b32 s56, 0
	s_barrier
	v_readlane_b32 s57, v251, 17
	v_readlane_b32 s64, v251, 24
	v_readlane_b32 s65, v251, 25
	v_readlane_b32 s66, v251, 26
	v_readlane_b32 s67, v251, 27
	v_readlane_b32 s68, v251, 28
	v_readlane_b32 s69, v251, 29
	v_readlane_b32 s70, v251, 30
	v_readlane_b32 s71, v251, 31
	s_branch .LBB9_225

; #define PG8_STAGE(bufoff, gbase, voff) do { _Pragma("unroll") for (int _i = 0; _i < 2; ++_i) \
;         __builtin_amdgcn_global_load_lds((const unsigned*)((const char*)(gbase) + (voff)[_i]), (PG8_LAS unsigned*)(lds + (bufoff) + ldsw + _i * 8192), 16, 0, 0); } while (0)
; #define PG8_WAIT_V(n) asm volatile("s_waitcnt vmcnt(" #n ")" ::: "memory")
; #define PG8_BAR __builtin_amdgcn_s_barrier()
; template <class Epi, class Sched, bool ALIGN_EPI = false, bool SP2 = false>
; __device__ __forceinline__ void gemm_phase(PG8_LAS unsigned char* lds, const Gemm g, const Sched& S, const Epi& E) {
;     ...
;     f32x4 acc[2][2][4][2];
; #pragma unroll
;     for (int a = 0; a < 2; ++a)
; #pragma unroll
;         for (int b = 0; b < 2; ++b)
; #pragma unroll
;             for (int m = 0; m < 4; ++m)
; #pragma unroll
;                 for (int n = 0; n < 2; ++n) acc[a][b][m][n] = (f32x4){0.f, 0.f, 0.f, 0.f};
;     ...
;     if constexpr (SP2) {
;         PG8_STAGE(PG8_SB(0, 0), cB, voffB); PG8_STAGE(PG8_SB(0, 1), cB + hstep, voffB); PG8_STAGE(PG8_SA(0, 0), cA, voffA); PG8_STAGE(PG8_SA(0, 1), cA + hstep, voffA);
;         if (wr == 1) PG8_BAR;
;         PG8_WAIT_V(2); PG8_BAR;
;         PG8_STAGE(PG8_SB(1, 0), cB + kstep, voffB); PG8_STAGE(PG8_SA(1, 0), cA + kstep, voffA); PG8_STAGE(PG8_SB(1, 1), cB + hstep + kstep, voffB);
;         PG8_WAIT_V(6); PG8_BAR;
.LBB9_508:
	s_add_u32 s10, s90, 0x8300000
	s_addc_u32 s11, s91, 0
	s_add_u32 s12, s90, 0x4200000
	s_addc_u32 s13, s91, 0
	s_add_u32 s45, s90, 0x2000000
	s_addc_u32 s46, s91, 0
	s_add_u32 s47, s90, 0x900000
	v_and_b32_e32 v13, 15, v208
	v_lshlrev_b32_e32 v14, 1, v11
	v_lshlrev_b32_e32 v15, 2, v208
	s_addc_u32 s48, s91, 0
	v_lshl_or_b32 v150, s0, 6, v13
	v_lshl_or_b32 v13, v13, 6, v14
	s_lshl_b32 s0, s0, 13
	v_and_b32_e32 v15, 32, v15
	v_bitop3_b32 v13, v13, s0, v15 bitop3:0xde
	s_lshl_b32 s0, s1, 5
	s_mov_b64 s[14:15], 0x80
	s_and_b32 s2, s0, 0x60
	v_lshlrev_b32_e32 v16, 6, v208
	s_movk_i32 s0, 0x3c0
	s_add_i32 m0, s27, 0x18000
	v_lshl_add_u64 v[6:7], v[6:7], 0, s[14:15]
	v_and_or_b32 v14, v16, s0, v14
	s_lshl_b32 s0, s2, 7
	global_load_lds_dwordx4 v[6:7], off
	v_lshl_add_u64 v[4:5], v[4:5], 0, s[14:15]
	s_add_i32 m0, s27, 0x1a000
	s_add_i32 s49, s27, 0x8000
	s_add_i32 s50, s27, 0xa000
	v_bitop3_b32 v151, s0, v14, v15 bitop3:0xf6
	global_load_lds_dwordx4 v[4:5], off
	v_lshl_add_u64 v[0:1], v[0:1], 0, s[14:15]
	s_mov_b32 m0, s49
	s_add_u32 s0, s34, 0x40080
	global_load_lds_dwordx4 v[0:1], off
	v_lshl_add_u64 v[0:1], v[2:3], 0, s[14:15]
	s_mov_b32 m0, s50
	s_addc_u32 s1, s35, 0
	global_load_lds_dwordx4 v[0:1], off
	s_add_i32 m0, s27, 0x1c000
	v_lshl_add_u64 v[0:1], s[0:1], 0, v[130:131]
	global_load_lds_dwordx4 v[0:1], off
	v_lshl_add_u64 v[0:1], s[0:1], 0, v[134:135]
	s_add_i32 m0, s27, 0x1e000
	s_cmpk_lt_u32 s16, 0x100
	global_load_lds_dwordx4 v[0:1], off
	s_waitcnt vmcnt(8)
	s_barrier
	v_lshlrev_b32_e32 v0, 8, v208
	v_and_b32_e32 v0, 0x38000, v0
	v_lshlrev_b32_e32 v1, 11, v10
	v_or3_b32 v0, v8, v0, v1
	v_add_u32_e32 v136, v0, v9
	v_lshlrev_b32_e32 v0, 4, v12
	s_waitcnt vmcnt(6)
	v_and_b32_e32 v0, 0x78000, v0
	v_or3_b32 v0, v8, v0, v1
	s_cselect_b64 s[16:17], -1, 0
	v_or_b32_e32 v152, 16, v150
	v_or_b32_e32 v153, 32, v150
	v_or_b32_e32 v154, 48, v150
	v_add_u32_e32 v155, 0x80, v150
	v_add_u32_e32 v156, 0x90, v150
	v_add_u32_e32 v157, 0xa0, v150
	v_add_u32_e32 v158, 0xb0, v150
	s_ashr_i32 s51, s97, 31
	v_or_b32_e32 v159, s2, v11
	v_mov_b32_e32 v137, v131
	v_add_u32_e32 v138, v0, v9
	v_mov_b32_e32 v139, v131
	v_mov_b64_e32 v[140:141], 0x100
	v_mov_b64_e32 v[142:143], 0xff
	s_add_i32 s52, 0, 0x10000
	s_add_i32 s53, 0, 0x14000
	v_add_u32_e32 v160, 0, v13
	s_mov_b32 s54, 0
	v_mov_b32_e32 v0, v131
	v_mov_b32_e32 v1, v131
	v_mov_b32_e32 v2, v131
	v_mov_b32_e32 v3, v131
	v_mov_b32_e32 v4, v131
	v_mov_b32_e32 v5, v131
	v_mov_b32_e32 v6, v131
	v_mov_b32_e32 v7, v131
	v_mov_b32_e32 v8, v131
	v_mov_b32_e32 v9, v131
	v_mov_b32_e32 v10, v131
	v_mov_b32_e32 v11, v131
	v_mov_b32_e32 v12, v131
	v_mov_b32_e32 v13, v131
	v_mov_b32_e32 v14, v131
	v_mov_b32_e32 v15, v131
	v_mov_b32_e32 v16, v131
	v_mov_b32_e32 v17, v131
	v_mov_b32_e32 v18, v131
	v_mov_b32_e32 v19, v131
	v_mov_b32_e32 v20, v131
	v_mov_b32_e32 v21, v131
	v_mov_b32_e32 v22, v131
	v_mov_b32_e32 v23, v131
	v_mov_b32_e32 v24, v131
	v_mov_b32_e32 v25, v131
	v_mov_b32_e32 v26, v131
	v_mov_b32_e32 v27, v131
	v_mov_b32_e32 v28, v131
	v_mov_b32_e32 v29, v131
	v_mov_b32_e32 v30, v131
	v_mov_b32_e32 v31, v131
	v_mov_b32_e32 v32, v131
	v_mov_b32_e32 v33, v131
	v_mov_b32_e32 v34, v131
	v_mov_b32_e32 v35, v131
	v_mov_b32_e32 v36, v131
	v_mov_b32_e32 v37, v131
	v_mov_b32_e32 v38, v131
	v_mov_b32_e32 v39, v131
	v_mov_b32_e32 v40, v131
	v_mov_b32_e32 v41, v131
	v_mov_b32_e32 v42, v131
	v_mov_b32_e32 v43, v131
	v_mov_b32_e32 v44, v131
	v_mov_b32_e32 v45, v131
	v_mov_b32_e32 v46, v131
	v_mov_b32_e32 v47, v131
	v_mov_b32_e32 v48, v131
	v_mov_b32_e32 v49, v131
	v_mov_b32_e32 v50, v131
	v_mov_b32_e32 v51, v131
	v_mov_b32_e32 v52, v131
	v_mov_b32_e32 v53, v131
	v_mov_b32_e32 v54, v131
	v_mov_b32_e32 v55, v131
	v_mov_b32_e32 v56, v131
	v_mov_b32_e32 v57, v131
	v_mov_b32_e32 v58, v131
	v_mov_b32_e32 v59, v131
	v_mov_b32_e32 v60, v131
	v_mov_b32_e32 v61, v131
	v_mov_b32_e32 v62, v131
	v_mov_b32_e32 v63, v131
	v_mov_b32_e32 v64, v131
	v_mov_b32_e32 v65, v131
	v_mov_b32_e32 v66, v131
	v_mov_b32_e32 v67, v131
	v_mov_b32_e32 v68, v131
	v_mov_b32_e32 v69, v131
	v_mov_b32_e32 v70, v131
	v_mov_b32_e32 v71, v131
	v_mov_b32_e32 v72, v131
	v_mov_b32_e32 v73, v131
	v_mov_b32_e32 v74, v131
	v_mov_b32_e32 v75, v131
	v_mov_b32_e32 v76, v131
	v_mov_b32_e32 v77, v131
	v_mov_b32_e32 v78, v131
	v_mov_b32_e32 v79, v131
	v_mov_b32_e32 v80, v131
	v_mov_b32_e32 v81, v131
	v_mov_b32_e32 v82, v131
	v_mov_b32_e32 v83, v131
	v_mov_b32_e32 v84, v131
	v_mov_b32_e32 v85, v131
	v_mov_b32_e32 v86, v131
	v_mov_b32_e32 v87, v131
	v_mov_b32_e32 v88, v131
	v_mov_b32_e32 v89, v131
	v_mov_b32_e32 v90, v131
	v_mov_b32_e32 v91, v131
	v_mov_b32_e32 v92, v131
	v_mov_b32_e32 v93, v131
	v_mov_b32_e32 v94, v131
	v_mov_b32_e32 v95, v131
	v_mov_b32_e32 v96, v131
	v_mov_b32_e32 v97, v131
	v_mov_b32_e32 v98, v131
	v_mov_b32_e32 v99, v131
	v_mov_b32_e32 v100, v131
	v_mov_b32_e32 v101, v131
	v_mov_b32_e32 v102, v131
	v_mov_b32_e32 v103, v131
	v_mov_b32_e32 v104, v131
	v_mov_b32_e32 v105, v131
	v_mov_b32_e32 v106, v131
	v_mov_b32_e32 v107, v131
	v_mov_b32_e32 v108, v131
	v_mov_b32_e32 v109, v131
	v_mov_b32_e32 v110, v131
	v_mov_b32_e32 v111, v131
	v_mov_b32_e32 v112, v131
	v_mov_b32_e32 v113, v131
	v_mov_b32_e32 v114, v131
	v_mov_b32_e32 v115, v131
	v_mov_b32_e32 v116, v131
	v_mov_b32_e32 v117, v131
	v_mov_b32_e32 v118, v131
	v_mov_b32_e32 v119, v131
	v_mov_b32_e32 v120, v131
	v_mov_b32_e32 v121, v131
	v_mov_b32_e32 v122, v131
	v_mov_b32_e32 v123, v131
	v_mov_b32_e32 v124, v131
	v_mov_b32_e32 v125, v131
	v_mov_b32_e32 v126, v131
	v_mov_b32_e32 v127, v131
	s_barrier
	s_branch .LBB9_511

; #define PG8_STAGE(bufoff, gbase, voff) do { _Pragma("unroll") for (int _i = 0; _i < 2; ++_i) \
;         __builtin_amdgcn_global_load_lds((const unsigned*)((const char*)(gbase) + (voff)[_i]), (PG8_LAS unsigned*)(lds + (bufoff) + ldsw + _i * 8192), 16, 0, 0); } while (0)
; #define PG8_WAIT_V(n) asm volatile("s_waitcnt vmcnt(" #n ")" ::: "memory")
; #define PG8_BAR __builtin_amdgcn_s_barrier()
; template <class Epi, class Sched, bool ALIGN_EPI = false, bool SP2 = false>
; __device__ __forceinline__ void gemm_phase(PG8_LAS unsigned char* lds, const Gemm g, const Sched& S, const Epi& E) {
;     const int tid = threadIdx.x, wid = __builtin_amdgcn_readfirstlane(tid >> 6), lane = tid & 63, wr = wid >> 2, wc = wid & 3, fr = lane & 15, fq = lane >> 4;
;     const int K = g.K, nt1 = K / BK, nt0 = g.K0 ? g.K0 / BK : nt1;
;     unsigned voffA[2], voffB[2];
; #pragma unroll
;     for (int i = 0; i < 2; ++i) { int R, C; stage_rc(tid * 16 + i * 8192, R, C); const int Rb = Epi::PERM ? ((R & ~31) + perm32(R & 31)) : R;
;         voffA[i] = (unsigned)(R * K + C) * 2u; voffB[i] = (unsigned)(Rb * K + C) * 2u; }
;     const size_t kstep = (size_t)(BK * 2);
;     const size_t hstep = (size_t)HALF * K * 2;
;     const size_t tstep = 2 * hstep;
;     const unsigned ldsw = (unsigned)wid * 1024u;
;     const int aoff = lds_byte(wr * 64 + fr, fq * 8), boff = lds_byte(wc * 32 + fr, fq * 8);
;     ...
;     if constexpr (SP2) {
;         PG8_STAGE(PG8_SB(0, 0), cB, voffB); PG8_STAGE(PG8_SB(0, 1), cB + hstep, voffB); PG8_STAGE(PG8_SA(0, 0), cA, voffA); PG8_STAGE(PG8_SA(0, 1), cA + hstep, voffA);
;         if (wr == 1) PG8_BAR;
;         PG8_WAIT_V(2); PG8_BAR;
;         PG8_STAGE(PG8_SB(1, 0), cB + kstep, voffB); PG8_STAGE(PG8_SA(1, 0), cA + kstep, voffA); PG8_STAGE(PG8_SB(1, 1), cB + hstep + kstep, voffB);
;         PG8_WAIT_V(6); PG8_BAR;
.LBB9_655:
	s_add_u32 s48, s90, 0x1f40000
	s_addc_u32 s49, s91, 0
	s_add_u32 s14, s90, 0xe300000
	s_addc_u32 s15, s91, 0
	s_add_u32 s16, s90, 0x2000000
	s_mov_b64 s[18:19], 0x80
	s_addc_u32 s17, s91, 0
	s_and_b32 s1, s1, 3
	s_add_i32 m0, s31, 0x18000
	v_lshl_add_u64 v[6:7], v[6:7], 0, s[18:19]
	s_lshl_b32 s5, s0, 13
	s_lshl_b32 s6, s1, 12
	global_load_lds_dwordx4 v[6:7], off
	v_lshl_add_u64 v[4:5], v[4:5], 0, s[18:19]
	s_add_i32 m0, s31, 0x1a000
	s_add_i32 s50, s31, 0x8000
	s_add_i32 s51, s31, 0xa000
	global_load_lds_dwordx4 v[4:5], off
	v_lshl_add_u64 v[0:1], v[0:1], 0, s[18:19]
	s_mov_b32 m0, s50
	s_add_u32 s2, s36, 0x40080
	global_load_lds_dwordx4 v[0:1], off
	v_lshl_add_u64 v[0:1], v[2:3], 0, s[18:19]
	s_mov_b32 m0, s51
	s_addc_u32 s3, s37, 0
	global_load_lds_dwordx4 v[0:1], off
	s_add_i32 m0, s31, 0x1c000
	v_lshl_add_u64 v[0:1], s[2:3], 0, v[162:163]
	global_load_lds_dwordx4 v[0:1], off
	v_lshl_add_u64 v[0:1], s[2:3], 0, v[166:167]
	s_add_i32 m0, s31, 0x1e000
	v_lshlrev_b32_e32 v5, 6, v208
	global_load_lds_dwordx4 v[0:1], off
	s_waitcnt vmcnt(8)
	s_barrier
	v_and_b32_e32 v0, 15, v208
	v_bfe_u32 v1, v208, 4, 2
	v_lshl_or_b32 v209, s0, 6, v0
	v_lshlrev_b32_e32 v2, 3, v1
	v_lshlrev_b32_e32 v3, 4, v1
	s_movk_i32 s0, 0x3c0
	s_cmpk_lt_u32 s4, 0x100
	v_lshl_or_b32 v0, v0, 6, v3
	v_and_or_b32 v3, v5, s0, v3
	v_lshl_or_b32 v211, s1, 5, v2
	s_cselect_b64 s[20:21], -1, 0
	s_lshl_b32 s3, s1, 2
	v_cmp_eq_u32_e64 s[0:1], 0, v1
	v_lshlrev_b32_e32 v1, 8, v208
	v_and_b32_e32 v1, 0x38000, v1
	v_lshlrev_b32_e32 v2, 11, v10
	v_lshlrev_b32_e32 v4, 2, v208
	v_or3_b32 v1, v8, v1, v2
	v_and_b32_e32 v4, 32, v4
	s_movk_i32 s2, 0x100
	v_add_u32_e32 v168, v1, v9
	v_lshlrev_b32_e32 v1, 4, v11
	v_bitop3_b32 v0, v0, s5, v4 bitop3:0xde
	s_waitcnt vmcnt(6)
	v_cmp_gt_u32_e64 s[4:5], s2, v208
	s_add_i32 s2, 0, 0x20000
	v_and_b32_e32 v1, 0x78000, v1
	v_bitop3_b32 v210, s6, v3, v4 bitop3:0xf6
	s_add_i32 s3, s3, s2
	v_or3_b32 v1, v8, v1, v2
	s_add_i32 s55, 0, 0x10000
	s_add_i32 s56, 0, 0x14000
	v_add_u32_e32 v216, 0, v0
	v_mbcnt_lo_u32_b32 v0, -1, 0
	s_ashr_i32 s52, s94, 31
	s_mov_b32 s53, s94
	s_ashr_i32 s54, s97, 31
	v_lshl_add_u32 v212, v209, 5, s3
	v_lshl_add_u32 v213, v208, 5, s2
	v_mov_b32_e32 v169, v163
	v_add_u32_e32 v170, v1, v9
	v_mov_b32_e32 v171, v163
	v_mov_b64_e32 v[172:173], 0x100
	v_mov_b64_e32 v[174:175], 0xff
	v_add_u32_e32 v214, s55, v210
	v_add_u32_e32 v215, s56, v210
	v_mbcnt_hi_u32_b32 v217, -1, v0
	s_barrier
	s_branch .LBB9_658

; #define PG8_STAGE(bufoff, gbase, voff) do { _Pragma("unroll") for (int _i = 0; _i < 2; ++_i) \
;         __builtin_amdgcn_global_load_lds((const unsigned*)((const char*)(gbase) + (voff)[_i]), (PG8_LAS unsigned*)(lds + (bufoff) + ldsw + _i * 8192), 16, 0, 0); } while (0)
; #define PG8_WAIT_V(n) asm volatile("s_waitcnt vmcnt(" #n ")" ::: "memory")
; #define PG8_BAR __builtin_amdgcn_s_barrier()
; template <class Epi, class Sched, bool ALIGN_EPI = false, bool SP2 = false>
; __device__ __forceinline__ void gemm_phase(PG8_LAS unsigned char* lds, const Gemm g, const Sched& S, const Epi& E) {
;     const int tid = threadIdx.x, wid = __builtin_amdgcn_readfirstlane(tid >> 6), lane = tid & 63, wr = wid >> 2, wc = wid & 3, fr = lane & 15, fq = lane >> 4;
;     const int K = g.K, nt1 = K / BK, nt0 = g.K0 ? g.K0 / BK : nt1;
;     unsigned voffA[2], voffB[2];
; #pragma unroll
;     for (int i = 0; i < 2; ++i) { int R, C; stage_rc(tid * 16 + i * 8192, R, C); const int Rb = Epi::PERM ? ((R & ~31) + perm32(R & 31)) : R;
;         voffA[i] = (unsigned)(R * K + C) * 2u; voffB[i] = (unsigned)(Rb * K + C) * 2u; }
;     const size_t kstep = (size_t)(BK * 2);
;     const size_t hstep = (size_t)HALF * K * 2;
;     const size_t tstep = 2 * hstep;
;     const unsigned ldsw = (unsigned)wid * 1024u;
;     const int aoff = lds_byte(wr * 64 + fr, fq * 8), boff = lds_byte(wc * 32 + fr, fq * 8);
;     ...
;     if constexpr (SP2) {
;         PG8_STAGE(PG8_SB(0, 0), cB, voffB); PG8_STAGE(PG8_SB(0, 1), cB + hstep, voffB); PG8_STAGE(PG8_SA(0, 0), cA, voffA); PG8_STAGE(PG8_SA(0, 1), cA + hstep, voffA);
;         if (wr == 1) PG8_BAR;
;         PG8_WAIT_V(2); PG8_BAR;
;         PG8_STAGE(PG8_SB(1, 0), cB + kstep, voffB); PG8_STAGE(PG8_SA(1, 0), cA + kstep, voffA); PG8_STAGE(PG8_SB(1, 1), cB + hstep + kstep, voffB);
;         PG8_WAIT_V(6); PG8_BAR;
.LBB9_764:
	s_add_u32 s8, s90, 0xe300000
	s_addc_u32 s9, s91, 0
	s_add_u32 s10, s90, 0x4200000
	s_addc_u32 s11, s91, 0
	s_add_u32 s44, s90, 0x1f80000
	s_addc_u32 s45, s91, 0
	s_lshl_b32 s3, s3, 5
	s_mov_b64 s[12:13], 0x80
	s_and_b32 s3, s3, 0x60
	s_add_i32 m0, s25, 0x18000
	v_lshl_add_u64 v[8:9], v[8:9], 0, s[12:13]
	s_lshl_b32 s16, s2, 13
	s_lshl_b32 s17, s3, 7
	global_load_lds_dwordx4 v[8:9], off
	v_lshl_add_u64 v[6:7], v[6:7], 0, s[12:13]
	s_add_i32 m0, s25, 0x1a000
	s_add_i32 s46, s25, 0x8000
	s_add_i32 s47, s25, 0xa000
	global_load_lds_dwordx4 v[6:7], off
	v_lshl_add_u64 v[2:3], v[2:3], 0, s[12:13]
	s_mov_b32 m0, s46
	s_add_u32 s14, s28, 0x40080
	global_load_lds_dwordx4 v[2:3], off
	v_lshl_add_u64 v[2:3], v[4:5], 0, s[12:13]
	s_mov_b32 m0, s47
	s_addc_u32 s15, s29, 0
	global_load_lds_dwordx4 v[2:3], off
	s_add_i32 m0, s25, 0x1c000
	v_lshl_add_u64 v[2:3], s[14:15], 0, v[148:149]
	global_load_lds_dwordx4 v[2:3], off
	v_lshl_add_u64 v[2:3], s[14:15], 0, v[144:145]
	s_add_i32 m0, s25, 0x1e000
	s_sext_i32_i16 s54, s0
	global_load_lds_dwordx4 v[2:3], off
	s_waitcnt vmcnt(8)
	s_barrier
	v_and_b32_e32 v2, 15, v208
	v_lshlrev_b32_e32 v3, 1, v0
	v_lshlrev_b32_e32 v4, 2, v208
	v_lshlrev_b32_e32 v5, 6, v208
	s_movk_i32 s0, 0x3c0
	v_lshl_or_b32 v166, s2, 6, v2
	v_lshl_or_b32 v2, v2, 6, v3
	v_and_b32_e32 v4, 32, v4
	v_and_or_b32 v3, v5, s0, v3
	v_bitop3_b32 v167, s17, v3, v4 bitop3:0xf6
	v_lshlrev_b32_e32 v3, 8, v208
	v_lshlrev_b32_e32 v1, 4, v1
	v_bitop3_b32 v2, v2, s16, v4 bitop3:0xde
	s_waitcnt vmcnt(6)
	s_cmpk_lt_u32 s1, 0x100
	v_and_b32_e32 v3, 0x38000, v3
	v_lshlrev_b32_e32 v4, 11, v12
	v_and_b32_e32 v1, 0x78000, v1
	s_cselect_b64 s[14:15], -1, 0
	v_or3_b32 v3, v10, v3, v4
	v_or3_b32 v1, v10, v1, v4
	s_add_i32 s50, 0, 0x10000
	s_add_i32 s51, 0, 0x14000
	s_ashr_i32 s48, s94, 31
	s_mov_b32 s49, s94
	v_or_b32_e32 v168, s3, v0
	v_add_u32_e32 v152, v3, v11
	v_mov_b32_e32 v153, v149
	v_add_u32_e32 v154, v1, v11
	v_mov_b32_e32 v155, v149
	v_mov_b64_e32 v[156:157], 0x580
	v_mov_b64_e32 v[158:159], 0x57f
	v_add_u32_e32 v169, s50, v167
	v_add_u32_e32 v170, s51, v167
	v_add_u32_e32 v171, 0, v2
	s_lshl_b32 s52, s3, 2
	v_lshlrev_b32_e32 v172, 2, v0
	v_mov_b32_e32 v173, 0x358637bd
	s_movk_i32 s53, 0x1600
	s_barrier
	s_branch .LBB9_767

; #define PG8_STAGE(bufoff, gbase, voff) do { _Pragma("unroll") for (int _i = 0; _i < 2; ++_i) \
;         __builtin_amdgcn_global_load_lds((const unsigned*)((const char*)(gbase) + (voff)[_i]), (PG8_LAS unsigned*)(lds + (bufoff) + ldsw + _i * 8192), 16, 0, 0); } while (0)
; #define PG8_WAIT_V(n) asm volatile("s_waitcnt vmcnt(" #n ")" ::: "memory")
; #define PG8_BAR __builtin_amdgcn_s_barrier()
; template <class Epi, class Sched, bool ALIGN_EPI = false, bool SP2 = false>
; __device__ __forceinline__ void gemm_phase(PG8_LAS unsigned char* lds, const Gemm g, const Sched& S, const Epi& E) {
;     const int tid = threadIdx.x, wid = __builtin_amdgcn_readfirstlane(tid >> 6), lane = tid & 63, wr = wid >> 2, wc = wid & 3, fr = lane & 15, fq = lane >> 4;
;     const int K = g.K, nt1 = K / BK, nt0 = g.K0 ? g.K0 / BK : nt1;
;     unsigned voffA[2], voffB[2];
; #pragma unroll
;     for (int i = 0; i < 2; ++i) { int R, C; stage_rc(tid * 16 + i * 8192, R, C); const int Rb = Epi::PERM ? ((R & ~31) + perm32(R & 31)) : R;
;         voffA[i] = (unsigned)(R * K + C) * 2u; voffB[i] = (unsigned)(Rb * K + C) * 2u; }
;     const size_t kstep = (size_t)(BK * 2);
;     const size_t hstep = (size_t)HALF * K * 2;
;     const size_t tstep = 2 * hstep;
;     const unsigned ldsw = (unsigned)wid * 1024u;
;     const int aoff = lds_byte(wr * 64 + fr, fq * 8), boff = lds_byte(wc * 32 + fr, fq * 8);
;     ...
;     if constexpr (SP2) {
;         PG8_STAGE(PG8_SB(0, 0), cB, voffB); PG8_STAGE(PG8_SB(0, 1), cB + hstep, voffB); PG8_STAGE(PG8_SA(0, 0), cA, voffA); PG8_STAGE(PG8_SA(0, 1), cA + hstep, voffA);
;         if (wr == 1) PG8_BAR;
;         PG8_WAIT_V(2); PG8_BAR;
;         PG8_STAGE(PG8_SB(1, 0), cB + kstep, voffB); PG8_STAGE(PG8_SA(1, 0), cA + kstep, voffA); PG8_STAGE(PG8_SB(1, 1), cB + hstep + kstep, voffB);
;         PG8_WAIT_V(6); PG8_BAR;
.LBB9_839:
	s_lshl_b32 s5, s5, 5
	s_mov_b64 s[8:9], 0x80
	s_and_b32 s5, s5, 0x60
	s_add_i32 m0, s24, 0x18000
	v_lshl_add_u64 v[6:7], v[6:7], 0, s[8:9]
	s_lshl_b32 s12, s0, 13
	s_lshl_b32 s13, s5, 7
	global_load_lds_dwordx4 v[6:7], off
	v_lshl_add_u64 v[4:5], v[4:5], 0, s[8:9]
	s_add_i32 m0, s24, 0x1a000
	s_add_i32 s29, s24, 0x8000
	s_add_i32 s30, s24, 0xa000
	global_load_lds_dwordx4 v[4:5], off
	v_lshl_add_u64 v[0:1], v[0:1], 0, s[8:9]
	s_mov_b32 m0, s29
	s_add_u32 s10, s16, 0xb0080
	global_load_lds_dwordx4 v[0:1], off
	v_lshl_add_u64 v[0:1], v[2:3], 0, s[8:9]
	s_mov_b32 m0, s30
	s_addc_u32 s11, s17, 0
	global_load_lds_dwordx4 v[0:1], off
	s_add_i32 m0, s24, 0x1c000
	v_lshl_add_u64 v[0:1], s[10:11], 0, v[138:139]
	global_load_lds_dwordx4 v[0:1], off
	v_lshl_add_u64 v[0:1], s[10:11], 0, v[142:143]
	s_add_i32 m0, s24, 0x1e000
	v_lshlrev_b32_e32 v2, 2, v208
	global_load_lds_dwordx4 v[0:1], off
	s_waitcnt vmcnt(8)
	s_barrier
	v_and_b32_e32 v0, 15, v208
	v_lshl_or_b32 v170, s0, 6, v0
	v_lshlrev_b32_e32 v1, 1, v10
	v_lshlrev_b32_e32 v3, 6, v208
	s_movk_i32 s0, 0x3c0
	v_lshl_or_b32 v0, v0, 6, v1
	v_and_b32_e32 v2, 32, v2
	v_and_or_b32 v1, v3, s0, v1
	v_bitop3_b32 v171, s13, v1, v2 bitop3:0xf6
	s_waitcnt vmcnt(6)
	s_cmpk_lt_u32 s4, 0x100
	v_add_u16_e32 v1, v8, v9
	v_bitop3_b32 v0, v0, s12, v2 bitop3:0xde
	s_cselect_b64 s[10:11], -1, 0
	v_lshrrev_b16_e32 v1, 1, v1
	s_add_i32 s33, 0, 0x10000
	s_add_i32 s34, 0, 0x14000
	s_sext_i32_i8 s38, s1
	s_ashr_i32 s31, s94, 31
	v_or_b32_e32 v172, s5, v10
	v_add_lshl_u32 v144, v11, v1, 1
	v_mov_b32_e32 v145, v139
	v_add_lshl_u32 v146, v12, v1, 1
	v_mov_b32_e32 v147, v139
	v_mov_b64_e32 v[148:149], 0x100
	v_mov_b64_e32 v[150:151], 0xff
	v_add_u32_e32 v173, s33, v171
	v_add_u32_e32 v174, s34, v171
	v_add_u32_e32 v175, 0, v0
	s_barrier
	s_branch .LBB9_842
